# v17_post
# speedup vs baseline: 1.0317x; 1.0165x over previous
; #define STAGE(PP, RSRC, br, kt) do { const int _so = ((br) * K + (kt) * BK) * 2; \
;       __builtin_amdgcn_raw_ptr_buffer_load_lds(RSRC, LDSP((char*)(PP) + ldsoff), 16, voff0, _so, 0, 0); \
;       __builtin_amdgcn_raw_ptr_buffer_load_lds(RSRC, LDSP((char*)(PP) + ldsoff + 8192), 16, voff1, _so, 0, 0); \
;     } while (0)
; #define LDA(dst, b, h) for (int m = 0; m < 4; ++m) for (int k = 0; k < 2; ++k) \
;     dst[m][k] = *reinterpret_cast<const bf16x8*>((char*)SA(b, h) + lds_byte(wr * 64 + m * 16 + fr, k * 32 + fq * 8))
; #define LDB(dst, b, h) for (int n = 0; n < 2; ++n) for (int k = 0; k < 2; ++k) \
;     dst[n][k] = *reinterpret_cast<const bf16x8*>((char*)SB(b, h) + lds_byte(wc * 32 + n * 16 + fr, k * 32 + fq * 8))
; #define MMA(ai, bj, At_, Bt_) do { __builtin_amdgcn_s_setprio(1); \
;     for (int m = 0; m < 4; ++m) for (int n = 0; n < 2; ++n) for (int k = 0; k < 2; ++k) \
;       acc[ai][bj][m][n] = __builtin_amdgcn_mfma_f32_16x16x32_bf16(At_[m][k], Bt_[n][k], acc[ai][bj][m][n], 0, 0, 0); \
;     __builtin_amdgcn_s_setprio(0); } while (0)
; #define WAIT_V(n) asm volatile("s_waitcnt vmcnt(" #n ")" ::: "memory")
; #define WAIT_L(n) asm volatile("s_waitcnt lgkmcnt(" #n ")" ::: "memory")
; #define BAR __builtin_amdgcn_s_barrier()
; #define SCHED __builtin_amdgcn_sched_barrier(0)
; __device__ __forceinline__ void gemm_tile(const Params& P, const GArgs& ga, const TileDesc& td, int wid_s) {
;     ...
;   for (int t = 0; t < nt - 2; t += 2) {
;     LDA(At, 0, 0); STAGE(SA(1, 1), A, brow + HALF, t + 1);
;     WAIT_L(8); BAR; WAIT_L(0); MMA(0, 0, At, B0); BAR; SCHED;
;     LDB(B1, 0, 1); STAGE(SB(0, 0), Bt, bcol, t + 2);
;     BAR; WAIT_L(0); MMA(0, 1, At, B1); BAR;
;     LDA(At, 0, 1); STAGE(SA(0, 0), A, brow, t + 2);
;     WAIT_V(4); BAR; WAIT_L(0); MMA(1, 0, At, B0); BAR; SCHED;
;     LDB(B0, 1, 0); STAGE(SB(0, 1), Bt, bcol + HALF, t + 2);
;     BAR; MMA(1, 1, At, B1); BAR;
;     LDA(At, 1, 0); STAGE(SA(0, 1), A, brow + HALF, t + 2);
;     WAIT_L(8); BAR; WAIT_L(0); MMA(0, 0, At, B0); BAR; SCHED;
.LBB0_306:
	s_andn2_b64 vcc, exec, s[0:1]
	v_mov_b32_e32 v141, 0
	s_cbranch_vccnz .LBB0_310
	v_and_b32_e32 v22, 0x3c0, v22
	v_and_b32_e32 v23, 32, v23
	v_bitop3_b32 v150, v22, v23, v18 bitop3:0x36
	v_lshlrev_b32_e32 v23, 6, v21
	v_lshlrev_b32_e32 v21, 2, v21
	v_and_b32_e32 v23, 0x3c0, v23
	v_and_b32_e32 v21, 32, v21
	v_bitop3_b32 v152, v23, v21, v18 bitop3:0x36
	v_lshlrev_b32_e32 v23, 6, v20
	v_lshlrev_b32_e32 v20, 2, v20
	v_and_b32_e32 v23, 0x3c0, v23
	v_and_b32_e32 v20, 32, v20
	s_add_i32 s1, 0, 0x14000
	v_bitop3_b32 v154, v23, v20, v18 bitop3:0x36
	v_lshlrev_b32_e32 v23, 6, v19
	v_lshlrev_b32_e32 v19, 2, v19
	v_add_u32_e32 v24, s1, v146
	s_add_i32 s1, 0, 0x18000
	v_and_b32_e32 v23, 0x3c0, v23
	v_and_b32_e32 v19, 32, v19
	v_add_u32_e32 v25, s1, v146
	s_add_i32 s1, 0, 0x1c000
	v_bitop3_b32 v156, v23, v19, v18 bitop3:0x36
	v_add_u32_e32 v26, s1, v146
	v_add_u32_e32 v22, 0, v150
	v_add_u32_e32 v21, 0, v152
	v_add_u32_e32 v20, 0, v154
	v_add_u32_e32 v19, 0, v156
	s_add_i32 s1, s84, 0x80
	s_add_i32 s6, s92, 0x80
	v_mov_b32_e32 v18, 0
	s_add_i32 s0, s17, -2
	v_or_b32_e32 v151, 0x400, v159
	v_or_b32_e32 v153, 0x400, v161
	v_or_b32_e32 v155, 0x400, v160
	v_or_b32_e32 v157, 0x400, v158
	s_mul_i32 s1, s48, s1
	s_mul_i32 s98, s48, s6
	s_mov_b32 s99, 0
	v_add_u32_e32 v163, v22, v159
	v_add_u32_e32 v164, v21, v161
	v_add_u32_e32 v165, v20, v160
	v_add_u32_e32 v166, v19, v158
	v_add_u32_e32 v167, v24, v147
	v_add_u32_e32 v168, v25, v147
	v_add_u32_e32 v169, v26, v147
	s_mov_b32 vcc_lo, 0
	s_waitcnt vmcnt(15)
	s_waitcnt vmcnt(14)
	s_add_i32 s38, s1, s99
	s_add_i32 s6, s38, 0x80
	s_mov_b32 m0, s23
	ds_read_b128 v[170:173], v163
	ds_read_b128 v[174:177], v163 offset:1024
	ds_read_b128 v[178:181], v164
	ds_read_b128 v[182:185], v164 offset:1024
	ds_read_b128 v[186:189], v165
	ds_read_b128 v[190:193], v165 offset:1024
	ds_read_b128 v[194:197], v166
	ds_read_b128 v[204:207], v166 offset:1024
	buffer_load_dwordx4 v148, s[8:11], s6 offen lds
	s_mov_b32 m0, s22
	s_nop 0
	buffer_load_dwordx4 v149, s[8:11], s6 offen lds
	s_mul_i32 s6, s49, s15
	s_add_i32 s58, s6, s99
	s_mov_b32 m0, s88
	s_add_i32 vcc_hi, s58, 0x100
	s_mov_b32 s6, s10
	s_mov_b32 s7, s11
	ds_read_b128 v[208:211], v167
	ds_read_b128 v[212:215], v167 offset:1024
	ds_read_b128 v[216:219], v167 offset:2048
	ds_read_b128 v[220:223], v167 offset:3072
	buffer_load_dwordx4 v148, s[4:7], vcc_hi offen lds
	s_mov_b32 m0, s89
	s_add_i32 vcc_lo, vcc_lo, 2
	buffer_load_dwordx4 v149, s[4:7], vcc_hi offen lds
	s_waitcnt vmcnt(8) lgkmcnt(0)
	s_barrier
	s_setprio 1
	v_mfma_f32_16x16x32_bf16 v[138:141], v[170:173], v[2:5], 0
	v_mfma_f32_16x16x32_bf16 v[142:145], v[170:173], v[10:13], 0
	v_mfma_f32_16x16x32_bf16 v[134:137], v[178:181], v[2:5], 0
	v_mfma_f32_16x16x32_bf16 v[130:133], v[178:181], v[10:13], 0
	v_mfma_f32_16x16x32_bf16 v[126:129], v[186:189], v[2:5], 0
	v_mfma_f32_16x16x32_bf16 v[122:125], v[186:189], v[10:13], 0
	v_mfma_f32_16x16x32_bf16 v[118:121], v[194:197], v[2:5], 0
	v_mfma_f32_16x16x32_bf16 v[114:117], v[194:197], v[10:13], 0
	v_mfma_f32_16x16x32_bf16 v[138:141], v[174:177], v[6:9], v[138:141]
	v_mfma_f32_16x16x32_bf16 v[142:145], v[174:177], v[14:17], v[142:145]
	v_mfma_f32_16x16x32_bf16 v[134:137], v[182:185], v[6:9], v[134:137]
	v_mfma_f32_16x16x32_bf16 v[130:133], v[182:185], v[14:17], v[130:133]
	v_mfma_f32_16x16x32_bf16 v[126:129], v[190:193], v[6:9], v[126:129]
	v_mfma_f32_16x16x32_bf16 v[122:125], v[190:193], v[14:17], v[122:125]
	v_mfma_f32_16x16x32_bf16 v[118:121], v[204:207], v[6:9], v[118:121]
	v_mfma_f32_16x16x32_bf16 v[114:117], v[204:207], v[14:17], v[114:117]
	v_mfma_f32_16x16x32_bf16 v[110:113], v[170:173], v[208:211], 0
	v_mfma_f32_16x16x32_bf16 v[106:109], v[170:173], v[216:219], 0
	v_mfma_f32_16x16x32_bf16 v[102:105], v[178:181], v[208:211], 0
	v_mfma_f32_16x16x32_bf16 v[98:101], v[178:181], v[216:219], 0
	v_mfma_f32_16x16x32_bf16 v[94:97], v[186:189], v[208:211], 0
	v_mfma_f32_16x16x32_bf16 v[90:93], v[186:189], v[216:219], 0
	v_mfma_f32_16x16x32_bf16 v[86:89], v[194:197], v[208:211], 0
	v_mfma_f32_16x16x32_bf16 v[82:85], v[194:197], v[216:219], 0
	v_mfma_f32_16x16x32_bf16 v[110:113], v[174:177], v[212:215], v[110:113]
	v_mfma_f32_16x16x32_bf16 v[106:109], v[174:177], v[220:223], v[106:109]
	v_mfma_f32_16x16x32_bf16 v[102:105], v[182:185], v[212:215], v[102:105]
	v_mfma_f32_16x16x32_bf16 v[98:101], v[182:185], v[220:223], v[98:101]
	v_mfma_f32_16x16x32_bf16 v[94:97], v[190:193], v[212:215], v[94:97]
	v_mfma_f32_16x16x32_bf16 v[90:93], v[190:193], v[220:223], v[90:93]
	v_mfma_f32_16x16x32_bf16 v[86:89], v[204:207], v[212:215], v[86:89]
	v_mfma_f32_16x16x32_bf16 v[82:85], v[204:207], v[220:223], v[82:85]
	s_setprio 0
	s_barrier
	s_mul_i32 vcc_hi, s49, s86
	s_add_i32 s40, vcc_hi, s99
	s_add_i32 vcc_hi, s40, 0x100
	s_mov_b32 m0, s52
	ds_read_b128 v[170:173], v163 offset:16384
	ds_read_b128 v[174:177], v163 offset:17408
	ds_read_b128 v[178:181], v164 offset:16384
	ds_read_b128 v[182:185], v164 offset:17408
	ds_read_b128 v[186:189], v165 offset:16384
	ds_read_b128 v[190:193], v165 offset:17408
	ds_read_b128 v[194:197], v166 offset:16384
	ds_read_b128 v[204:207], v166 offset:17408
	buffer_load_dwordx4 v148, s[8:11], vcc_hi offen lds
	s_mov_b32 m0, s94
	s_nop 0
	buffer_load_dwordx4 v149, s[8:11], vcc_hi offen lds
	s_add_i32 s33, s98, s99
	s_add_i32 vcc_hi, s33, 0x100
	s_mov_b32 m0, s95
	ds_read_b128 v[232:235], v168
	ds_read_b128 v[236:239], v168 offset:1024
	ds_read_b128 v[240:243], v168 offset:2048
	ds_read_b128 v[244:247], v168 offset:3072
	buffer_load_dwordx4 v148, s[4:7], vcc_hi offen lds
	s_mov_b32 m0, s3
	s_nop 0
	buffer_load_dwordx4 v149, s[4:7], vcc_hi offen lds
	s_waitcnt vmcnt(8) lgkmcnt(0)
	s_barrier
; #define STAGE(PP, RSRC, br, kt) do { const int _so = ((br) * K + (kt) * BK) * 2; \
;       __builtin_amdgcn_raw_ptr_buffer_load_lds(RSRC, LDSP((char*)(PP) + ldsoff), 16, voff0, _so, 0, 0); \
;       __builtin_amdgcn_raw_ptr_buffer_load_lds(RSRC, LDSP((char*)(PP) + ldsoff + 8192), 16, voff1, _so, 0, 0); \
;     } while (0)
; #define LDA(dst, b, h) for (int m = 0; m < 4; ++m) for (int k = 0; k < 2; ++k) \
;     dst[m][k] = *reinterpret_cast<const bf16x8*>((char*)SA(b, h) + lds_byte(wr * 64 + m * 16 + fr, k * 32 + fq * 8))
; #define LDB(dst, b, h) for (int n = 0; n < 2; ++n) for (int k = 0; k < 2; ++k) \
;     dst[n][k] = *reinterpret_cast<const bf16x8*>((char*)SB(b, h) + lds_byte(wc * 32 + n * 16 + fr, k * 32 + fq * 8))
; #define MMA(ai, bj, At_, Bt_) do { __builtin_amdgcn_s_setprio(1); \
;     for (int m = 0; m < 4; ++m) for (int n = 0; n < 2; ++n) for (int k = 0; k < 2; ++k) \
;       acc[ai][bj][m][n] = __builtin_amdgcn_mfma_f32_16x16x32_bf16(At_[m][k], Bt_[n][k], acc[ai][bj][m][n], 0, 0, 0); \
;     __builtin_amdgcn_s_setprio(0); } while (0)
; #define WAIT_V(n) asm volatile("s_waitcnt vmcnt(" #n ")" ::: "memory")
; #define WAIT_L(n) asm volatile("s_waitcnt lgkmcnt(" #n ")" ::: "memory")
; #define BAR __builtin_amdgcn_s_barrier()
; #define SCHED __builtin_amdgcn_sched_barrier(0)
; __device__ __forceinline__ void gemm_tile(const Params& P, const GArgs& ga, const TileDesc& td, int wid_s) {
;     ...
;     WAIT_V(4); BAR; WAIT_L(0); MMA(1, 0, At, B0); BAR; SCHED;
;     LDB(B0, 1, 0); STAGE(SB(0, 1), Bt, bcol + HALF, t + 2);
;     BAR; MMA(1, 1, At, B1); BAR;
;     LDA(At, 1, 0); STAGE(SA(0, 1), A, brow + HALF, t + 2);
;     WAIT_L(8); BAR; WAIT_L(0); MMA(0, 0, At, B0); BAR; SCHED;
;     LDB(B1, 1, 1); STAGE(SB(1, 0), Bt, bcol, t + 3);
;     BAR; WAIT_L(0); MMA(0, 1, At, B1); BAR;
	s_setprio 1
	v_mfma_f32_16x16x32_bf16 v[78:81], v[170:173], v[2:5], 0
	v_mfma_f32_16x16x32_bf16 v[70:73], v[178:181], v[2:5], 0
	v_mfma_f32_16x16x32_bf16 v[62:65], v[186:189], v[2:5], 0
	v_mfma_f32_16x16x32_bf16 v[248:251], v[194:197], v[2:5], 0
	v_mfma_f32_16x16x32_bf16 v[78:81], v[174:177], v[6:9], v[78:81]
	v_mfma_f32_16x16x32_bf16 v[74:77], v[170:173], v[10:13], 0
	v_mfma_f32_16x16x32_bf16 v[70:73], v[182:185], v[6:9], v[70:73]
	v_mfma_f32_16x16x32_bf16 v[66:69], v[178:181], v[10:13], 0
	v_mfma_f32_16x16x32_bf16 v[62:65], v[190:193], v[6:9], v[62:65]
	v_mfma_f32_16x16x32_bf16 v[58:61], v[186:189], v[10:13], 0
	v_mfma_f32_16x16x32_bf16 v[248:251], v[204:207], v[6:9], v[248:251]
	v_mfma_f32_16x16x32_bf16 v[252:255], v[194:197], v[10:13], 0
	v_mfma_f32_16x16x32_bf16 v[74:77], v[174:177], v[14:17], v[74:77]
	v_mfma_f32_16x16x32_bf16 v[66:69], v[182:185], v[14:17], v[66:69]
	v_mfma_f32_16x16x32_bf16 v[58:61], v[190:193], v[14:17], v[58:61]
	v_mfma_f32_16x16x32_bf16 v[252:255], v[204:207], v[14:17], v[252:255]
	v_mfma_f32_16x16x32_bf16 v[46:49], v[170:173], v[208:211], 0
	v_mfma_f32_16x16x32_bf16 v[42:45], v[170:173], v[216:219], 0
	v_mfma_f32_16x16x32_bf16 v[38:41], v[178:181], v[208:211], 0
	v_mfma_f32_16x16x32_bf16 v[34:37], v[178:181], v[216:219], 0
	v_mfma_f32_16x16x32_bf16 v[30:33], v[186:189], v[208:211], 0
	v_mfma_f32_16x16x32_bf16 v[26:29], v[186:189], v[216:219], 0
	v_mfma_f32_16x16x32_bf16 v[22:25], v[194:197], v[208:211], 0
	v_mfma_f32_16x16x32_bf16 v[18:21], v[194:197], v[216:219], 0
	v_mfma_f32_16x16x32_bf16 v[46:49], v[174:177], v[212:215], v[46:49]
	v_mfma_f32_16x16x32_bf16 v[42:45], v[174:177], v[220:223], v[42:45]
	v_mfma_f32_16x16x32_bf16 v[38:41], v[182:185], v[212:215], v[38:41]
	v_mfma_f32_16x16x32_bf16 v[34:37], v[182:185], v[220:223], v[34:37]
	v_mfma_f32_16x16x32_bf16 v[30:33], v[190:193], v[212:215], v[30:33]
	v_mfma_f32_16x16x32_bf16 v[26:29], v[190:193], v[220:223], v[26:29]
	v_mfma_f32_16x16x32_bf16 v[22:25], v[204:207], v[212:215], v[22:25]
	v_mfma_f32_16x16x32_bf16 v[18:21], v[204:207], v[220:223], v[18:21]
	s_setprio 0
	s_barrier
	s_addk_i32 s38, 0x100
	s_mov_b32 m0, s57
	ds_read_b128 v[54:57], v163 offset:32768
	ds_read_b128 v[170:173], v163 offset:33792
	ds_read_b128 v[174:177], v164 offset:32768
	ds_read_b128 v[178:181], v164 offset:33792
	ds_read_b128 v[182:185], v165 offset:32768
	ds_read_b128 v[186:189], v165 offset:33792
	ds_read_b128 v[190:193], v166 offset:32768
	ds_read_b128 v[194:197], v166 offset:33792
	buffer_load_dwordx4 v148, s[8:11], s38 offen lds
	s_mov_b32 m0, s56
	s_nop 0
	buffer_load_dwordx4 v149, s[8:11], s38 offen lds
	s_addk_i32 s58, 0x180
	s_mov_b32 m0, s75
	ds_read_b128 v[204:207], v169
	ds_read_b128 v[208:211], v169 offset:1024
	ds_read_b128 v[212:215], v169 offset:2048
	ds_read_b128 v[216:219], v169 offset:3072
	buffer_load_dwordx4 v148, s[4:7], s58 offen lds
	s_mov_b32 m0, s74
	s_nop 0
	buffer_load_dwordx4 v149, s[4:7], s58 offen lds
	s_waitcnt vmcnt(8) lgkmcnt(0)
	s_barrier
	s_setprio 1
	v_mfma_f32_16x16x32_bf16 v[138:141], v[54:57], v[232:235], v[138:141]
	v_mfma_f32_16x16x32_bf16 v[142:145], v[54:57], v[240:243], v[142:145]
	v_mfma_f32_16x16x32_bf16 v[134:137], v[174:177], v[232:235], v[134:137]
	v_mfma_f32_16x16x32_bf16 v[130:133], v[174:177], v[240:243], v[130:133]
	v_mfma_f32_16x16x32_bf16 v[126:129], v[182:185], v[232:235], v[126:129]
	v_mfma_f32_16x16x32_bf16 v[122:125], v[182:185], v[240:243], v[122:125]
	v_mfma_f32_16x16x32_bf16 v[118:121], v[190:193], v[232:235], v[118:121]
	v_mfma_f32_16x16x32_bf16 v[114:117], v[190:193], v[240:243], v[114:117]
	v_mfma_f32_16x16x32_bf16 v[138:141], v[170:173], v[236:239], v[138:141]
	v_mfma_f32_16x16x32_bf16 v[142:145], v[170:173], v[244:247], v[142:145]
	v_mfma_f32_16x16x32_bf16 v[134:137], v[178:181], v[236:239], v[134:137]
	v_mfma_f32_16x16x32_bf16 v[130:133], v[178:181], v[244:247], v[130:133]
	v_mfma_f32_16x16x32_bf16 v[126:129], v[186:189], v[236:239], v[126:129]
	v_mfma_f32_16x16x32_bf16 v[122:125], v[186:189], v[244:247], v[122:125]
	v_mfma_f32_16x16x32_bf16 v[118:121], v[194:197], v[236:239], v[118:121]
	v_mfma_f32_16x16x32_bf16 v[114:117], v[194:197], v[244:247], v[114:117]
	v_mfma_f32_16x16x32_bf16 v[110:113], v[54:57], v[204:207], v[110:113]
	v_mfma_f32_16x16x32_bf16 v[54:57], v[54:57], v[212:215], v[106:109]
	v_mfma_f32_16x16x32_bf16 v[106:109], v[170:173], v[216:219], v[54:57]
	v_mfma_f32_16x16x32_bf16 v[54:57], v[174:177], v[204:207], v[102:105]
	v_mfma_f32_16x16x32_bf16 v[102:105], v[178:181], v[208:211], v[54:57]
	v_mfma_f32_16x16x32_bf16 v[54:57], v[174:177], v[212:215], v[98:101]
	v_mfma_f32_16x16x32_bf16 v[98:101], v[178:181], v[216:219], v[54:57]
	v_mfma_f32_16x16x32_bf16 v[54:57], v[182:185], v[204:207], v[94:97]
	v_mfma_f32_16x16x32_bf16 v[94:97], v[186:189], v[208:211], v[54:57]
	v_mfma_f32_16x16x32_bf16 v[54:57], v[182:185], v[212:215], v[90:93]
	v_mfma_f32_16x16x32_bf16 v[90:93], v[186:189], v[216:219], v[54:57]
	v_mfma_f32_16x16x32_bf16 v[54:57], v[190:193], v[204:207], v[86:89]
	v_mfma_f32_16x16x32_bf16 v[86:89], v[194:197], v[208:211], v[54:57]
	v_mfma_f32_16x16x32_bf16 v[54:57], v[190:193], v[212:215], v[82:85]
	v_mfma_f32_16x16x32_bf16 v[110:113], v[170:173], v[208:211], v[110:113]
	v_mfma_f32_16x16x32_bf16 v[82:85], v[194:197], v[216:219], v[54:57]
	s_setprio 0
	s_barrier
; #define STAGE(PP, RSRC, br, kt) do { const int _so = ((br) * K + (kt) * BK) * 2; \
;       __builtin_amdgcn_raw_ptr_buffer_load_lds(RSRC, LDSP((char*)(PP) + ldsoff), 16, voff0, _so, 0, 0); \
;       __builtin_amdgcn_raw_ptr_buffer_load_lds(RSRC, LDSP((char*)(PP) + ldsoff + 8192), 16, voff1, _so, 0, 0); \
;     } while (0)
; #define LDA(dst, b, h) for (int m = 0; m < 4; ++m) for (int k = 0; k < 2; ++k) \
;     dst[m][k] = *reinterpret_cast<const bf16x8*>((char*)SA(b, h) + lds_byte(wr * 64 + m * 16 + fr, k * 32 + fq * 8))
; #define LDB(dst, b, h) for (int n = 0; n < 2; ++n) for (int k = 0; k < 2; ++k) \
;     dst[n][k] = *reinterpret_cast<const bf16x8*>((char*)SB(b, h) + lds_byte(wc * 32 + n * 16 + fr, k * 32 + fq * 8))
; #define MMA(ai, bj, At_, Bt_) do { __builtin_amdgcn_s_setprio(1); \
;     for (int m = 0; m < 4; ++m) for (int n = 0; n < 2; ++n) for (int k = 0; k < 2; ++k) \
;       acc[ai][bj][m][n] = __builtin_amdgcn_mfma_f32_16x16x32_bf16(At_[m][k], Bt_[n][k], acc[ai][bj][m][n], 0, 0, 0); \
;     __builtin_amdgcn_s_setprio(0); } while (0)
; #define WAIT_V(n) asm volatile("s_waitcnt vmcnt(" #n ")" ::: "memory")
; #define WAIT_L(n) asm volatile("s_waitcnt lgkmcnt(" #n ")" ::: "memory")
; #define BAR __builtin_amdgcn_s_barrier()
; #define SCHED __builtin_amdgcn_sched_barrier(0)
; __device__ __forceinline__ void gemm_tile(const Params& P, const GArgs& ga, const TileDesc& td, int wid_s) {
;     ...
;   for (int t = 0; t < nt - 2; t += 2) {
;     LDA(At, 0, 0); STAGE(SA(1, 1), A, brow + HALF, t + 1);
;     WAIT_L(8); BAR; WAIT_L(0); MMA(0, 0, At, B0); BAR; SCHED;
;     LDB(B1, 0, 1); STAGE(SB(0, 0), Bt, bcol, t + 2);
;     BAR; WAIT_L(0); MMA(0, 1, At, B1); BAR;
;     ...
;     LDB(B1, 1, 1); STAGE(SB(1, 0), Bt, bcol, t + 3);
;     BAR; WAIT_L(0); MMA(0, 1, At, B1); BAR;
;     LDA(At, 1, 1); STAGE(SA(1, 0), A, brow, t + 3);
;     WAIT_V(4); BAR; WAIT_L(0); MMA(1, 0, At, B0); BAR; SCHED;
;     LDB(B0, 0, 0); STAGE(SB(1, 1), Bt, bcol + HALF, t + 3);
;     BAR; MMA(1, 1, At, B1); BAR;
;   }
	s_addk_i32 s40, 0x180
	s_mov_b32 m0, s83
	ds_read_b128 v[170:173], v163 offset:49152
	ds_read_b128 v[174:177], v163 offset:50176
	ds_read_b128 v[178:181], v164 offset:49152
	ds_read_b128 v[182:185], v164 offset:50176
	ds_read_b128 v[186:189], v165 offset:49152
	ds_read_b128 v[190:193], v165 offset:50176
	ds_read_b128 v[194:197], v166 offset:49152
	ds_read_b128 v[220:223], v166 offset:50176
	buffer_load_dwordx4 v148, s[8:11], s40 offen lds
	s_mov_b32 m0, s82
	s_nop 0
	buffer_load_dwordx4 v149, s[8:11], s40 offen lds
	s_mov_b32 m0, s69
	s_addk_i32 s33, 0x180
	buffer_load_dwordx4 v148, s[4:7], s33 offen lds
	s_mov_b32 m0, s68
	s_nop 0
	buffer_load_dwordx4 v149, s[4:7], s33 offen lds
	ds_read_b128 v[2:5], v162
	ds_read_b128 v[6:9], v162 offset:1024
	ds_read_b128 v[10:13], v162 offset:2048
	ds_read_b128 v[14:17], v162 offset:3072
	s_addk_i32 s99, 0x100
	s_cmp_lt_i32 vcc_lo, s0
	s_waitcnt vmcnt(8) lgkmcnt(0)
	s_barrier
	s_setprio 1
	v_mfma_f32_16x16x32_bf16 v[54:57], v[170:173], v[232:235], v[78:81]
	v_mfma_f32_16x16x32_bf16 v[78:81], v[174:177], v[236:239], v[54:57]
	v_mfma_f32_16x16x32_bf16 v[54:57], v[170:173], v[240:243], v[74:77]
	v_mfma_f32_16x16x32_bf16 v[74:77], v[174:177], v[244:247], v[54:57]
	v_mfma_f32_16x16x32_bf16 v[54:57], v[178:181], v[232:235], v[70:73]
	v_mfma_f32_16x16x32_bf16 v[70:73], v[182:185], v[236:239], v[54:57]
	v_mfma_f32_16x16x32_bf16 v[54:57], v[178:181], v[240:243], v[66:69]
	v_mfma_f32_16x16x32_bf16 v[66:69], v[182:185], v[244:247], v[54:57]
	v_mfma_f32_16x16x32_bf16 v[54:57], v[186:189], v[232:235], v[62:65]
	v_mfma_f32_16x16x32_bf16 v[62:65], v[190:193], v[236:239], v[54:57]
	v_mfma_f32_16x16x32_bf16 v[54:57], v[186:189], v[240:243], v[58:61]
	v_mfma_f32_16x16x32_bf16 v[248:251], v[194:197], v[232:235], v[248:251]
	v_mfma_f32_16x16x32_bf16 v[58:61], v[190:193], v[244:247], v[54:57]
	v_mfma_f32_16x16x32_bf16 v[54:57], v[220:223], v[236:239], v[248:251]
	v_mfma_f32_16x16x32_bf16 v[248:251], v[194:197], v[240:243], v[252:255]
	v_mfma_f32_16x16x32_bf16 v[50:53], v[220:223], v[244:247], v[248:251]
	v_mfma_f32_16x16x32_bf16 v[46:49], v[170:173], v[204:207], v[46:49]
	v_mfma_f32_16x16x32_bf16 v[42:45], v[170:173], v[212:215], v[42:45]
	v_mfma_f32_16x16x32_bf16 v[38:41], v[178:181], v[204:207], v[38:41]
	v_mfma_f32_16x16x32_bf16 v[34:37], v[178:181], v[212:215], v[34:37]
	v_mfma_f32_16x16x32_bf16 v[30:33], v[186:189], v[204:207], v[30:33]
	v_mfma_f32_16x16x32_bf16 v[26:29], v[186:189], v[212:215], v[26:29]
	v_mfma_f32_16x16x32_bf16 v[22:25], v[194:197], v[204:207], v[22:25]
	v_mfma_f32_16x16x32_bf16 v[18:21], v[194:197], v[212:215], v[18:21]
	v_mfma_f32_16x16x32_bf16 v[46:49], v[174:177], v[208:211], v[46:49]
	v_mfma_f32_16x16x32_bf16 v[42:45], v[174:177], v[216:219], v[42:45]
	v_mfma_f32_16x16x32_bf16 v[38:41], v[182:185], v[208:211], v[38:41]
	v_mfma_f32_16x16x32_bf16 v[34:37], v[182:185], v[216:219], v[34:37]
	v_mfma_f32_16x16x32_bf16 v[30:33], v[190:193], v[208:211], v[30:33]
	v_mfma_f32_16x16x32_bf16 v[26:29], v[190:193], v[216:219], v[26:29]
	v_mfma_f32_16x16x32_bf16 v[22:25], v[220:223], v[208:211], v[22:25]
	v_mfma_f32_16x16x32_bf16 v[18:21], v[220:223], v[216:219], v[18:21]
	s_setprio 0
	s_barrier
	s_cbranch_scc0 .Lml_exit
.LBB0_308:
	s_add_i32 s38, s1, s99
	s_add_i32 s6, s38, 0x80
	s_mov_b32 m0, s23
	ds_read_b128 v[170:173], v163
	ds_read_b128 v[174:177], v163 offset:1024
	ds_read_b128 v[178:181], v164
	ds_read_b128 v[182:185], v164 offset:1024
	ds_read_b128 v[186:189], v165
	ds_read_b128 v[190:193], v165 offset:1024
	ds_read_b128 v[194:197], v166
	ds_read_b128 v[204:207], v166 offset:1024
	buffer_load_dwordx4 v148, s[8:11], s6 offen lds
	s_mov_b32 m0, s22
	s_nop 0
	buffer_load_dwordx4 v149, s[8:11], s6 offen lds
	s_mul_i32 s6, s49, s15
	s_add_i32 s58, s6, s99
	s_mov_b32 m0, s88
	s_add_i32 vcc_hi, s58, 0x100
	s_mov_b32 s6, s10
	s_mov_b32 s7, s11
	ds_read_b128 v[208:211], v167
	ds_read_b128 v[212:215], v167 offset:1024
	ds_read_b128 v[216:219], v167 offset:2048
	ds_read_b128 v[220:223], v167 offset:3072
	buffer_load_dwordx4 v148, s[4:7], vcc_hi offen lds
	s_mov_b32 m0, s89
	s_add_i32 vcc_lo, vcc_lo, 2
	buffer_load_dwordx4 v149, s[4:7], vcc_hi offen lds
	s_waitcnt vmcnt(8) lgkmcnt(0)
	s_barrier
	s_setprio 1
	v_mfma_f32_16x16x32_bf16 v[138:141], v[170:173], v[2:5], v[138:141]
	v_mfma_f32_16x16x32_bf16 v[142:145], v[170:173], v[10:13], v[142:145]
	v_mfma_f32_16x16x32_bf16 v[134:137], v[178:181], v[2:5], v[134:137]
	v_mfma_f32_16x16x32_bf16 v[130:133], v[178:181], v[10:13], v[130:133]
	v_mfma_f32_16x16x32_bf16 v[126:129], v[186:189], v[2:5], v[126:129]
	v_mfma_f32_16x16x32_bf16 v[122:125], v[186:189], v[10:13], v[122:125]
	v_mfma_f32_16x16x32_bf16 v[118:121], v[194:197], v[2:5], v[118:121]
	v_mfma_f32_16x16x32_bf16 v[114:117], v[194:197], v[10:13], v[114:117]
	v_mfma_f32_16x16x32_bf16 v[138:141], v[174:177], v[6:9], v[138:141]
	v_mfma_f32_16x16x32_bf16 v[142:145], v[174:177], v[14:17], v[142:145]
	v_mfma_f32_16x16x32_bf16 v[134:137], v[182:185], v[6:9], v[134:137]
	v_mfma_f32_16x16x32_bf16 v[130:133], v[182:185], v[14:17], v[130:133]
	v_mfma_f32_16x16x32_bf16 v[126:129], v[190:193], v[6:9], v[126:129]
	v_mfma_f32_16x16x32_bf16 v[122:125], v[190:193], v[14:17], v[122:125]
	v_mfma_f32_16x16x32_bf16 v[118:121], v[204:207], v[6:9], v[118:121]
	v_mfma_f32_16x16x32_bf16 v[114:117], v[204:207], v[14:17], v[114:117]
	v_mfma_f32_16x16x32_bf16 v[110:113], v[170:173], v[208:211], v[110:113]
	v_mfma_f32_16x16x32_bf16 v[106:109], v[170:173], v[216:219], v[106:109]
	v_mfma_f32_16x16x32_bf16 v[102:105], v[178:181], v[208:211], v[102:105]
	v_mfma_f32_16x16x32_bf16 v[98:101], v[178:181], v[216:219], v[98:101]
	v_mfma_f32_16x16x32_bf16 v[94:97], v[186:189], v[208:211], v[94:97]
	v_mfma_f32_16x16x32_bf16 v[90:93], v[186:189], v[216:219], v[90:93]
	v_mfma_f32_16x16x32_bf16 v[86:89], v[194:197], v[208:211], v[86:89]
	v_mfma_f32_16x16x32_bf16 v[82:85], v[194:197], v[216:219], v[82:85]
	v_mfma_f32_16x16x32_bf16 v[110:113], v[174:177], v[212:215], v[110:113]
	v_mfma_f32_16x16x32_bf16 v[106:109], v[174:177], v[220:223], v[106:109]
	v_mfma_f32_16x16x32_bf16 v[102:105], v[182:185], v[212:215], v[102:105]
	v_mfma_f32_16x16x32_bf16 v[98:101], v[182:185], v[220:223], v[98:101]
	v_mfma_f32_16x16x32_bf16 v[94:97], v[190:193], v[212:215], v[94:97]
	v_mfma_f32_16x16x32_bf16 v[90:93], v[190:193], v[220:223], v[90:93]
	v_mfma_f32_16x16x32_bf16 v[86:89], v[204:207], v[212:215], v[86:89]
	v_mfma_f32_16x16x32_bf16 v[82:85], v[204:207], v[220:223], v[82:85]
	s_setprio 0
	s_barrier
; #define STAGE(PP, RSRC, br, kt) do { const int _so = ((br) * K + (kt) * BK) * 2; \
;       __builtin_amdgcn_raw_ptr_buffer_load_lds(RSRC, LDSP((char*)(PP) + ldsoff), 16, voff0, _so, 0, 0); \
;       __builtin_amdgcn_raw_ptr_buffer_load_lds(RSRC, LDSP((char*)(PP) + ldsoff + 8192), 16, voff1, _so, 0, 0); \
;     } while (0)
; #define LDA(dst, b, h) for (int m = 0; m < 4; ++m) for (int k = 0; k < 2; ++k) \
;     dst[m][k] = *reinterpret_cast<const bf16x8*>((char*)SA(b, h) + lds_byte(wr * 64 + m * 16 + fr, k * 32 + fq * 8))
; #define LDB(dst, b, h) for (int n = 0; n < 2; ++n) for (int k = 0; k < 2; ++k) \
;     dst[n][k] = *reinterpret_cast<const bf16x8*>((char*)SB(b, h) + lds_byte(wc * 32 + n * 16 + fr, k * 32 + fq * 8))
; #define MMA(ai, bj, At_, Bt_) do { __builtin_amdgcn_s_setprio(1); \
;     for (int m = 0; m < 4; ++m) for (int n = 0; n < 2; ++n) for (int k = 0; k < 2; ++k) \
;       acc[ai][bj][m][n] = __builtin_amdgcn_mfma_f32_16x16x32_bf16(At_[m][k], Bt_[n][k], acc[ai][bj][m][n], 0, 0, 0); \
;     __builtin_amdgcn_s_setprio(0); } while (0)
; #define WAIT_V(n) asm volatile("s_waitcnt vmcnt(" #n ")" ::: "memory")
; #define WAIT_L(n) asm volatile("s_waitcnt lgkmcnt(" #n ")" ::: "memory")
; #define BAR __builtin_amdgcn_s_barrier()
; #define SCHED __builtin_amdgcn_sched_barrier(0)
; __device__ __forceinline__ void gemm_tile(const Params& P, const GArgs& ga, const TileDesc& td, int wid_s) {
;     ...
;     BAR; WAIT_L(0); MMA(0, 1, At, B1); BAR;
;     LDA(At, 0, 1); STAGE(SA(0, 0), A, brow, t + 2);
;     WAIT_V(4); BAR; WAIT_L(0); MMA(1, 0, At, B0); BAR; SCHED;
;     LDB(B0, 1, 0); STAGE(SB(0, 1), Bt, bcol + HALF, t + 2);
;     BAR; MMA(1, 1, At, B1); BAR;
;     LDA(At, 1, 0); STAGE(SA(0, 1), A, brow + HALF, t + 2);
;     WAIT_L(8); BAR; WAIT_L(0); MMA(0, 0, At, B0); BAR; SCHED;
	s_mul_i32 vcc_hi, s49, s86
	s_add_i32 s40, vcc_hi, s99
	s_add_i32 vcc_hi, s40, 0x100
	s_mov_b32 m0, s52
	ds_read_b128 v[170:173], v163 offset:16384
	ds_read_b128 v[174:177], v163 offset:17408
	ds_read_b128 v[178:181], v164 offset:16384
	ds_read_b128 v[182:185], v164 offset:17408
	ds_read_b128 v[186:189], v165 offset:16384
	ds_read_b128 v[190:193], v165 offset:17408
	ds_read_b128 v[194:197], v166 offset:16384
	ds_read_b128 v[204:207], v166 offset:17408
	buffer_load_dwordx4 v148, s[8:11], vcc_hi offen lds
	s_mov_b32 m0, s94
	s_nop 0
	buffer_load_dwordx4 v149, s[8:11], vcc_hi offen lds
	s_add_i32 s33, s98, s99
	s_add_i32 vcc_hi, s33, 0x100
	s_mov_b32 m0, s95
	ds_read_b128 v[232:235], v168
	ds_read_b128 v[236:239], v168 offset:1024
	ds_read_b128 v[240:243], v168 offset:2048
	ds_read_b128 v[244:247], v168 offset:3072
	buffer_load_dwordx4 v148, s[4:7], vcc_hi offen lds
	s_mov_b32 m0, s3
	s_nop 0
	buffer_load_dwordx4 v149, s[4:7], vcc_hi offen lds
	s_waitcnt vmcnt(8) lgkmcnt(0)
	s_barrier
	s_setprio 1
	v_mfma_f32_16x16x32_bf16 v[78:81], v[170:173], v[2:5], v[78:81]
	v_mfma_f32_16x16x32_bf16 v[70:73], v[178:181], v[2:5], v[70:73]
	v_mfma_f32_16x16x32_bf16 v[62:65], v[186:189], v[2:5], v[62:65]
	v_mfma_f32_16x16x32_bf16 v[248:251], v[194:197], v[2:5], v[54:57]
	v_mfma_f32_16x16x32_bf16 v[78:81], v[174:177], v[6:9], v[78:81]
	v_mfma_f32_16x16x32_bf16 v[74:77], v[170:173], v[10:13], v[74:77]
	v_mfma_f32_16x16x32_bf16 v[70:73], v[182:185], v[6:9], v[70:73]
	v_mfma_f32_16x16x32_bf16 v[66:69], v[178:181], v[10:13], v[66:69]
	v_mfma_f32_16x16x32_bf16 v[62:65], v[190:193], v[6:9], v[62:65]
	v_mfma_f32_16x16x32_bf16 v[58:61], v[186:189], v[10:13], v[58:61]
	v_mfma_f32_16x16x32_bf16 v[248:251], v[204:207], v[6:9], v[248:251]
	v_mfma_f32_16x16x32_bf16 v[252:255], v[194:197], v[10:13], v[50:53]
	v_mfma_f32_16x16x32_bf16 v[74:77], v[174:177], v[14:17], v[74:77]
	v_mfma_f32_16x16x32_bf16 v[66:69], v[182:185], v[14:17], v[66:69]
	v_mfma_f32_16x16x32_bf16 v[58:61], v[190:193], v[14:17], v[58:61]
	v_mfma_f32_16x16x32_bf16 v[252:255], v[204:207], v[14:17], v[252:255]
	v_mfma_f32_16x16x32_bf16 v[46:49], v[170:173], v[208:211], v[46:49]
	v_mfma_f32_16x16x32_bf16 v[42:45], v[170:173], v[216:219], v[42:45]
	v_mfma_f32_16x16x32_bf16 v[38:41], v[178:181], v[208:211], v[38:41]
	v_mfma_f32_16x16x32_bf16 v[34:37], v[178:181], v[216:219], v[34:37]
	v_mfma_f32_16x16x32_bf16 v[30:33], v[186:189], v[208:211], v[30:33]
	v_mfma_f32_16x16x32_bf16 v[26:29], v[186:189], v[216:219], v[26:29]
	v_mfma_f32_16x16x32_bf16 v[22:25], v[194:197], v[208:211], v[22:25]
	v_mfma_f32_16x16x32_bf16 v[18:21], v[194:197], v[216:219], v[18:21]
	v_mfma_f32_16x16x32_bf16 v[46:49], v[174:177], v[212:215], v[46:49]
	v_mfma_f32_16x16x32_bf16 v[42:45], v[174:177], v[220:223], v[42:45]
	v_mfma_f32_16x16x32_bf16 v[38:41], v[182:185], v[212:215], v[38:41]
	v_mfma_f32_16x16x32_bf16 v[34:37], v[182:185], v[220:223], v[34:37]
	v_mfma_f32_16x16x32_bf16 v[30:33], v[190:193], v[212:215], v[30:33]
	v_mfma_f32_16x16x32_bf16 v[26:29], v[190:193], v[220:223], v[26:29]
	v_mfma_f32_16x16x32_bf16 v[22:25], v[204:207], v[212:215], v[22:25]
	v_mfma_f32_16x16x32_bf16 v[18:21], v[204:207], v[220:223], v[18:21]
	s_setprio 0
	s_barrier
	s_addk_i32 s38, 0x100
	s_mov_b32 m0, s57
	ds_read_b128 v[54:57], v163 offset:32768
	ds_read_b128 v[170:173], v163 offset:33792
	ds_read_b128 v[174:177], v164 offset:32768
	ds_read_b128 v[178:181], v164 offset:33792
	ds_read_b128 v[182:185], v165 offset:32768
	ds_read_b128 v[186:189], v165 offset:33792
	ds_read_b128 v[190:193], v166 offset:32768
	ds_read_b128 v[194:197], v166 offset:33792
	buffer_load_dwordx4 v148, s[8:11], s38 offen lds
	s_mov_b32 m0, s56
	s_nop 0
	buffer_load_dwordx4 v149, s[8:11], s38 offen lds
	s_addk_i32 s58, 0x180
	s_mov_b32 m0, s75
	ds_read_b128 v[204:207], v169
	ds_read_b128 v[208:211], v169 offset:1024
	ds_read_b128 v[212:215], v169 offset:2048
	ds_read_b128 v[216:219], v169 offset:3072
	buffer_load_dwordx4 v148, s[4:7], s58 offen lds
	s_mov_b32 m0, s74
	s_nop 0
	buffer_load_dwordx4 v149, s[4:7], s58 offen lds
	s_waitcnt vmcnt(8) lgkmcnt(0)
	s_barrier
; #define STAGE(PP, RSRC, br, kt) do { const int _so = ((br) * K + (kt) * BK) * 2; \
;       __builtin_amdgcn_raw_ptr_buffer_load_lds(RSRC, LDSP((char*)(PP) + ldsoff), 16, voff0, _so, 0, 0); \
;       __builtin_amdgcn_raw_ptr_buffer_load_lds(RSRC, LDSP((char*)(PP) + ldsoff + 8192), 16, voff1, _so, 0, 0); \
;     } while (0)
; #define LDA(dst, b, h) for (int m = 0; m < 4; ++m) for (int k = 0; k < 2; ++k) \
;     dst[m][k] = *reinterpret_cast<const bf16x8*>((char*)SA(b, h) + lds_byte(wr * 64 + m * 16 + fr, k * 32 + fq * 8))
; #define LDB(dst, b, h) for (int n = 0; n < 2; ++n) for (int k = 0; k < 2; ++k) \
;     dst[n][k] = *reinterpret_cast<const bf16x8*>((char*)SB(b, h) + lds_byte(wc * 32 + n * 16 + fr, k * 32 + fq * 8))
; #define MMA(ai, bj, At_, Bt_) do { __builtin_amdgcn_s_setprio(1); \
;     for (int m = 0; m < 4; ++m) for (int n = 0; n < 2; ++n) for (int k = 0; k < 2; ++k) \
;       acc[ai][bj][m][n] = __builtin_amdgcn_mfma_f32_16x16x32_bf16(At_[m][k], Bt_[n][k], acc[ai][bj][m][n], 0, 0, 0); \
;     __builtin_amdgcn_s_setprio(0); } while (0)
; #define WAIT_V(n) asm volatile("s_waitcnt vmcnt(" #n ")" ::: "memory")
; #define WAIT_L(n) asm volatile("s_waitcnt lgkmcnt(" #n ")" ::: "memory")
; #define BAR __builtin_amdgcn_s_barrier()
; #define SCHED __builtin_amdgcn_sched_barrier(0)
; __device__ __forceinline__ void gemm_tile(const Params& P, const GArgs& ga, const TileDesc& td, int wid_s) {
;     ...
;     LDA(At, 1, 0); STAGE(SA(0, 1), A, brow + HALF, t + 2);
;     WAIT_L(8); BAR; WAIT_L(0); MMA(0, 0, At, B0); BAR; SCHED;
;     LDB(B1, 1, 1); STAGE(SB(1, 0), Bt, bcol, t + 3);
;     BAR; WAIT_L(0); MMA(0, 1, At, B1); BAR;
;     LDA(At, 1, 1); STAGE(SA(1, 0), A, brow, t + 3);
;     WAIT_V(4); BAR; WAIT_L(0); MMA(1, 0, At, B0); BAR; SCHED;
;     LDB(B0, 0, 0); STAGE(SB(1, 1), Bt, bcol + HALF, t + 3);
;     BAR; MMA(1, 1, At, B1); BAR;
;   }
	s_setprio 1
	v_mfma_f32_16x16x32_bf16 v[138:141], v[54:57], v[232:235], v[138:141]
	v_mfma_f32_16x16x32_bf16 v[142:145], v[54:57], v[240:243], v[142:145]
	v_mfma_f32_16x16x32_bf16 v[134:137], v[174:177], v[232:235], v[134:137]
	v_mfma_f32_16x16x32_bf16 v[130:133], v[174:177], v[240:243], v[130:133]
	v_mfma_f32_16x16x32_bf16 v[126:129], v[182:185], v[232:235], v[126:129]
	v_mfma_f32_16x16x32_bf16 v[122:125], v[182:185], v[240:243], v[122:125]
	v_mfma_f32_16x16x32_bf16 v[118:121], v[190:193], v[232:235], v[118:121]
	v_mfma_f32_16x16x32_bf16 v[114:117], v[190:193], v[240:243], v[114:117]
	v_mfma_f32_16x16x32_bf16 v[138:141], v[170:173], v[236:239], v[138:141]
	v_mfma_f32_16x16x32_bf16 v[142:145], v[170:173], v[244:247], v[142:145]
	v_mfma_f32_16x16x32_bf16 v[134:137], v[178:181], v[236:239], v[134:137]
	v_mfma_f32_16x16x32_bf16 v[130:133], v[178:181], v[244:247], v[130:133]
	v_mfma_f32_16x16x32_bf16 v[126:129], v[186:189], v[236:239], v[126:129]
	v_mfma_f32_16x16x32_bf16 v[122:125], v[186:189], v[244:247], v[122:125]
	v_mfma_f32_16x16x32_bf16 v[118:121], v[194:197], v[236:239], v[118:121]
	v_mfma_f32_16x16x32_bf16 v[114:117], v[194:197], v[244:247], v[114:117]
	v_mfma_f32_16x16x32_bf16 v[110:113], v[54:57], v[204:207], v[110:113]
	v_mfma_f32_16x16x32_bf16 v[54:57], v[54:57], v[212:215], v[106:109]
	v_mfma_f32_16x16x32_bf16 v[106:109], v[170:173], v[216:219], v[54:57]
	v_mfma_f32_16x16x32_bf16 v[54:57], v[174:177], v[204:207], v[102:105]
	v_mfma_f32_16x16x32_bf16 v[102:105], v[178:181], v[208:211], v[54:57]
	v_mfma_f32_16x16x32_bf16 v[54:57], v[174:177], v[212:215], v[98:101]
	v_mfma_f32_16x16x32_bf16 v[98:101], v[178:181], v[216:219], v[54:57]
	v_mfma_f32_16x16x32_bf16 v[54:57], v[182:185], v[204:207], v[94:97]
	v_mfma_f32_16x16x32_bf16 v[94:97], v[186:189], v[208:211], v[54:57]
	v_mfma_f32_16x16x32_bf16 v[54:57], v[182:185], v[212:215], v[90:93]
	v_mfma_f32_16x16x32_bf16 v[90:93], v[186:189], v[216:219], v[54:57]
	v_mfma_f32_16x16x32_bf16 v[54:57], v[190:193], v[204:207], v[86:89]
	v_mfma_f32_16x16x32_bf16 v[86:89], v[194:197], v[208:211], v[54:57]
	v_mfma_f32_16x16x32_bf16 v[54:57], v[190:193], v[212:215], v[82:85]
	v_mfma_f32_16x16x32_bf16 v[110:113], v[170:173], v[208:211], v[110:113]
	v_mfma_f32_16x16x32_bf16 v[82:85], v[194:197], v[216:219], v[54:57]
	s_setprio 0
	s_barrier
	s_addk_i32 s40, 0x180
	s_mov_b32 m0, s83
	ds_read_b128 v[170:173], v163 offset:49152
	ds_read_b128 v[174:177], v163 offset:50176
	ds_read_b128 v[178:181], v164 offset:49152
	ds_read_b128 v[182:185], v164 offset:50176
	ds_read_b128 v[186:189], v165 offset:49152
	ds_read_b128 v[190:193], v165 offset:50176
	ds_read_b128 v[194:197], v166 offset:49152
	ds_read_b128 v[220:223], v166 offset:50176
	buffer_load_dwordx4 v148, s[8:11], s40 offen lds
	s_mov_b32 m0, s82
	s_nop 0
	buffer_load_dwordx4 v149, s[8:11], s40 offen lds
	s_mov_b32 m0, s69
	s_addk_i32 s33, 0x180
	buffer_load_dwordx4 v148, s[4:7], s33 offen lds
	s_mov_b32 m0, s68
	s_nop 0
	buffer_load_dwordx4 v149, s[4:7], s33 offen lds
	ds_read_b128 v[2:5], v162
	ds_read_b128 v[6:9], v162 offset:1024
	ds_read_b128 v[10:13], v162 offset:2048
	ds_read_b128 v[14:17], v162 offset:3072
	s_addk_i32 s99, 0x100
	s_cmp_lt_i32 vcc_lo, s0
	s_waitcnt vmcnt(8) lgkmcnt(0)
	s_barrier
	s_setprio 1
	v_mfma_f32_16x16x32_bf16 v[54:57], v[170:173], v[232:235], v[78:81]
	v_mfma_f32_16x16x32_bf16 v[78:81], v[174:177], v[236:239], v[54:57]
	v_mfma_f32_16x16x32_bf16 v[54:57], v[170:173], v[240:243], v[74:77]
	v_mfma_f32_16x16x32_bf16 v[74:77], v[174:177], v[244:247], v[54:57]
	v_mfma_f32_16x16x32_bf16 v[54:57], v[178:181], v[232:235], v[70:73]
	v_mfma_f32_16x16x32_bf16 v[70:73], v[182:185], v[236:239], v[54:57]
	v_mfma_f32_16x16x32_bf16 v[54:57], v[178:181], v[240:243], v[66:69]
	v_mfma_f32_16x16x32_bf16 v[66:69], v[182:185], v[244:247], v[54:57]
	v_mfma_f32_16x16x32_bf16 v[54:57], v[186:189], v[232:235], v[62:65]
	v_mfma_f32_16x16x32_bf16 v[62:65], v[190:193], v[236:239], v[54:57]
	v_mfma_f32_16x16x32_bf16 v[54:57], v[186:189], v[240:243], v[58:61]
	v_mfma_f32_16x16x32_bf16 v[248:251], v[194:197], v[232:235], v[248:251]
	v_mfma_f32_16x16x32_bf16 v[58:61], v[190:193], v[244:247], v[54:57]
	v_mfma_f32_16x16x32_bf16 v[54:57], v[220:223], v[236:239], v[248:251]
	v_mfma_f32_16x16x32_bf16 v[248:251], v[194:197], v[240:243], v[252:255]
	v_mfma_f32_16x16x32_bf16 v[50:53], v[220:223], v[244:247], v[248:251]
	v_mfma_f32_16x16x32_bf16 v[46:49], v[170:173], v[204:207], v[46:49]
	v_mfma_f32_16x16x32_bf16 v[42:45], v[170:173], v[212:215], v[42:45]
	v_mfma_f32_16x16x32_bf16 v[38:41], v[178:181], v[204:207], v[38:41]
	v_mfma_f32_16x16x32_bf16 v[34:37], v[178:181], v[212:215], v[34:37]
	v_mfma_f32_16x16x32_bf16 v[30:33], v[186:189], v[204:207], v[30:33]
	v_mfma_f32_16x16x32_bf16 v[26:29], v[186:189], v[212:215], v[26:29]
	v_mfma_f32_16x16x32_bf16 v[22:25], v[194:197], v[204:207], v[22:25]
	v_mfma_f32_16x16x32_bf16 v[18:21], v[194:197], v[212:215], v[18:21]
	v_mfma_f32_16x16x32_bf16 v[46:49], v[174:177], v[208:211], v[46:49]
	v_mfma_f32_16x16x32_bf16 v[42:45], v[174:177], v[216:219], v[42:45]
	v_mfma_f32_16x16x32_bf16 v[38:41], v[182:185], v[208:211], v[38:41]
	v_mfma_f32_16x16x32_bf16 v[34:37], v[182:185], v[216:219], v[34:37]
	v_mfma_f32_16x16x32_bf16 v[30:33], v[190:193], v[208:211], v[30:33]
	v_mfma_f32_16x16x32_bf16 v[26:29], v[190:193], v[216:219], v[26:29]
	v_mfma_f32_16x16x32_bf16 v[22:25], v[220:223], v[208:211], v[22:25]
	v_mfma_f32_16x16x32_bf16 v[18:21], v[220:223], v[216:219], v[18:21]
	s_setprio 0
	s_barrier
	s_cbranch_scc1 .LBB0_308
